# scan: static s_setprio 1 for the heavier wave of each SIMD pair (waves 4-7), reset after the item
# speedup vs baseline: 1.0166x; 1.0166x over previous
; #define BIDX bid_()
; #define GDIM gdim_()
; __device__ void phase_scan(const Params& p, int l, unsigned char* lds) {
;     for (int blk = BIDX; blk < 256; blk += GDIM) {
;         const int xcd = blk & 7, j = blk >> 3;
;         if (j < 16) scan_item<true>(p, l, (xcd + 8 * (j >> 2)) * 4 + (j & 3), lds);
;         else { const int G = xcd + 8 * ((j - 16) >> 3), r = (j - 16) & 7; const int dir = G & 1, g = (G >> 1) & 3, b = G >> 3;
;             scan_item<false>(p, l, dir + 2 * (g * 8 + r) + 64 * b, lds); }
;     }
.LBB0_19:
	s_setprio 0
	s_load_dword s3, s[0:1], 0xb8
	s_waitcnt lgkmcnt(0)
	s_add_i32 s68, s3, s68
	s_cmpk_gt_i32 s68, 0xff
	s_cbranch_scc1 .LBB0_253

; #define TIDX tid_()
; template <bool ISM>
; __device__ void scan_item(const Params& p, int l, int item, unsigned char* lds) {
;     constexpr int NT = ISM ? 5 : 4;
;     constexpr float L2E = 1.4426950408889634f;
;     const int tid = TIDX, wid = __builtin_amdgcn_readfirstlane(tid >> 6), lane = tid & 63, fr = lane & 15, fq = lane >> 4;
;     const int trq = fr >> 2, trp = fr & 3;
;     const int sl = ISM ? (item & 3) : 0, dir = ISM ? ((item >> 2) & 1) : (item & 1), h = ISM ? ((item >> 3) & 7) : ((item >> 1) & 31), b = item >> 6;
;     const int qcol = ISM ? h * 128 : 2048 + 2560 + (h >> 3) * 128;
;     const int kcol = ISM ? 1024 + h * 128 : 2048 + 2048 + (h >> 3) * 128;
;     const int vcol = ISM ? 2048 + h * 256 + sl * 64 : 2048 + h * 64;
;     const int ocol = ISM ? h * 256 + sl * 64 : h * 64;
.LBB0_27:
	s_or_b64 exec, exec, s[4:5]
	s_lshl_b32 s4, s8, 4
	s_and_b32 s4, s4, 0x180
	v_or_b32_e32 v1, s4, v25
	s_and_b32 s15, s68, 0xffffffc0
	v_or_b32_e32 v20, 0x1200, v1
	v_lshlrev_b32_e32 v1, 3, v24
	s_and_b32 s13, s68, 1
	s_addk_i32 s15, 0xff80
	s_ashr_i32 s18, s10, 6
	s_cmp_lt_i32 s18, 4
	s_cbranch_scc1 .Lwid_keep_s
	s_sub_i32 s18, 11, s18
	s_setprio 1

; #define TIDX tid_()
; template <bool ISM>
; __device__ void scan_item(const Params& p, int l, int item, unsigned char* lds) {
;     constexpr int NT = ISM ? 5 : 4;
;     constexpr float L2E = 1.4426950408889634f;
;     const int tid = TIDX, wid = __builtin_amdgcn_readfirstlane(tid >> 6), lane = tid & 63, fr = lane & 15, fq = lane >> 4;
;     const int trq = fr >> 2, trp = fr & 3;
;     const int sl = ISM ? (item & 3) : 0, dir = ISM ? ((item >> 2) & 1) : (item & 1), h = ISM ? ((item >> 3) & 7) : ((item >> 1) & 31), b = item >> 6;
;     const int qcol = ISM ? h * 128 : 2048 + 2560 + (h >> 3) * 128;
;     const int kcol = ISM ? 1024 + h * 128 : 2048 + 2048 + (h >> 3) * 128;
;     const int vcol = ISM ? 2048 + h * 256 + sl * 64 : 2048 + h * 64;
;     const int ocol = ISM ? h * 256 + sl * 64 : h * 64;
.LBB0_159:
	s_or_b64 exec, exec, s[4:5]
	s_lshl_b32 s3, s68, 2
	s_and_b32 s3, s3, 24
	s_and_b32 s4, s68, 32
	s_or_b32 s3, s3, s4
	s_lshl_b32 s5, s69, 6
	s_lshr_b32 s6, s3, 3
	s_lshl_b32 s4, s3, 4
	s_lshl_b32 s3, s3, 5
	s_and_b32 s5, s5, 0xc0
	v_lshlrev_b32_e32 v1, 3, v20
	s_ashr_i32 s16, s8, 6
	s_cmp_lt_i32 s16, 4
	s_cbranch_scc1 .Lwid_keep_m
	s_sub_i32 s16, 11, s16
	s_setprio 1
